# G1 k-loop head padded to a 64-byte boundary (4 s_nop before the loop label)
# baseline (speedup 1.0000x reference)
; #define PG8_STAGE(bufoff, gbase, voff) do { _Pragma("unroll") for (int _i = 0; _i < 2; ++_i) \
;         __builtin_amdgcn_global_load_lds((const unsigned*)((const char*)(gbase) + (voff)[_i]), (LAS unsigned*)(lds + (bufoff) + ldsw + _i * 8192), 16, 0, 0); } while (0)
; #define PG8_LDA(dst, b, h) do { _Pragma("unroll") for (int m = 0; m < 4; ++m) _Pragma("unroll") for (int k = 0; k < 2; ++k) dst[m][k] = *(const LAS bf16x8*)(lds + PG8_SA(b, h) + aoff + m * 2048 + k * 1024); } while (0)
; #define PG8_LDB(dst, b, h) do { _Pragma("unroll") for (int n = 0; n < 2; ++n) _Pragma("unroll") for (int k = 0; k < 2; ++k) dst[n][k] = *(const LAS bf16x8*)(lds + PG8_SB(b, h) + boff + n * 2048 + k * 1024); } while (0)
; #define PG8_MMA(ai, bj, At, Bt) do { __builtin_amdgcn_s_setprio(1); _Pragma("unroll") for (int m = 0; m < 4; ++m) _Pragma("unroll") for (int n = 0; n < 2; ++n) _Pragma("unroll") for (int k = 0; k < 2; ++k) \
;         acc[ai][bj][m][n] = __builtin_amdgcn_mfma_f32_16x16x32_bf16(Bt[n][k], At[m][k], acc[ai][bj][m][n], 0, 0, 0); __builtin_amdgcn_s_setprio(0); } while (0)
; #define PG8_WAIT_V(n) asm volatile("s_waitcnt vmcnt(" #n ")" ::: "memory")
; #define PG8_WAIT_L(n) asm volatile("s_waitcnt lgkmcnt(" #n ")" ::: "memory")
; #define PG8_BAR __builtin_amdgcn_s_barrier()
; #define PG8_SCHED __builtin_amdgcn_sched_barrier(0)
; template <class Epi>
; DI void gemm_phase(LAS unsigned char* lds, const Gemm g, int G, int c, const Epi& E) {
;     ...
;         for (int t = 0; t < nt; t += 2) {
;             const bool last = (t == nt - 2);
;             const char* a1 = cA + (size_t)(t + 1) * kstep;
;             const char* a2 = last ? nA : cA + (size_t)(t + 2) * kstep; const char* b2 = last ? nB : cB + (size_t)(t + 2) * kstep;
;             const char* a3 = a2 + kstep; const char* b3 = b2 + kstep;
;             PG8_LDB(B0, 0, 0); PG8_LDB(B1, 0, 1); PG8_SCHED; PG8_LDA(At, 0, 0); PG8_STAGE(PG8_SA(1, 1), a1 + hstepA, voffA);
;             PG8_WAIT_V(8); PG8_WAIT_L(0); PG8_BAR; PG8_MMA(0, 0, At, B0); PG8_MMA(0, 1, At, B1); PG8_BAR; PG8_SCHED;
;             PG8_LDA(At, 0, 1); PG8_STAGE(PG8_SB(0, 0), b2, voffB); PG8_STAGE(PG8_SB(0, 1), b2 + hstepB, voffB); PG8_STAGE(PG8_SA(0, 0), a2, voffA);
;             PG8_WAIT_V(8); PG8_WAIT_L(0); PG8_BAR; PG8_MMA(1, 0, At, B0); PG8_MMA(1, 1, At, B1); PG8_BAR; PG8_SCHED;
.LBB0_235:
	s_ashr_i32 s47, s46, 31
	s_lshl_b64 s[22:23], s[46:47], 19
	v_readlane_b32 s6, v250, 41
	s_add_u32 s50, s6, s22
	v_readlane_b32 s6, v250, 42
	s_addc_u32 s51, s6, s23
	s_and_b64 s[22:23], s[42:43], exec
	s_cselect_b32 s9, s51, s53
	s_cselect_b32 s11, s50, s52
	s_add_u32 s0, s0, 0x40080
	s_addc_u32 s1, s1, 0
	s_add_u32 s30, s52, 0x100
	s_addc_u32 s31, s53, 0
	s_mov_b32 s38, -2
	s_add_u32 s6, s0, 0xfffc0080
	s_addc_u32 s17, s1, -1
	s_add_i32 s18, 0, 0x10000
	s_cmp_eq_u32 s38, 12
	s_cselect_b32 s53, s49, s17
	s_cselect_b32 s52, s48, s6
	s_cselect_b32 s43, s9, s31
	s_cselect_b32 s42, s11, s30
	s_add_i32 s6, 0, 0x14000
	v_add_u32_e32 v172, s18, v155
	v_add_u32_e32 v188, s6, v155
	ds_read_b128 v[130:133], v172
	ds_read_b128 v[134:137], v172 offset:1024
	ds_read_b128 v[150:153], v172 offset:2048
	ds_read_b128 v[172:175], v172 offset:3072
	ds_read_b128 v[176:179], v188
	ds_read_b128 v[180:183], v188 offset:1024
	ds_read_b128 v[184:187], v188 offset:2048
	ds_read_b128 v[188:191], v188 offset:3072
	v_lshl_add_u64 v[200:201], s[0:1], 0, v[146:147]
	s_add_i32 m0, s79, 0xc000
	ds_read_b128 v[192:195], v163
	ds_read_b128 v[196:199], v163 offset:1024
	ds_read_b128 v[218:221], v163 offset:2048
	ds_read_b128 v[222:225], v163 offset:3072
	ds_read_b128 v[226:229], v163 offset:4096
	ds_read_b128 v[230:233], v163 offset:5120
	ds_read_b128 v[234:237], v163 offset:6144
	ds_read_b128 v[238:241], v163 offset:7168
	global_load_lds_dwordx4 v[200:201], off
	v_lshl_add_u64 v[200:201], s[0:1], 0, v[148:149]
	s_add_i32 m0, s79, 0xe000
	s_nop 0
	global_load_lds_dwordx4 v[200:201], off
	s_waitcnt vmcnt(8)
	s_waitcnt lgkmcnt(0)
	s_barrier
	s_setprio 1
	s_waitcnt lgkmcnt(0)
	v_mfma_f32_16x16x32_bf16 v[126:129], v[130:133], v[192:195], 0
	v_mfma_f32_16x16x32_bf16 v[122:125], v[150:153], v[192:195], 0
	v_mfma_f32_16x16x32_bf16 v[110:113], v[130:133], v[218:221], 0
	v_mfma_f32_16x16x32_bf16 v[106:109], v[150:153], v[218:221], 0
	v_mfma_f32_16x16x32_bf16 v[94:97], v[130:133], v[226:229], 0
	v_mfma_f32_16x16x32_bf16 v[90:93], v[150:153], v[226:229], 0
	v_mfma_f32_16x16x32_bf16 v[78:81], v[130:133], v[234:237], 0
	v_mfma_f32_16x16x32_bf16 v[74:77], v[150:153], v[234:237], 0
	v_mfma_f32_16x16x32_bf16 v[126:129], v[134:137], v[196:199], v[126:129]
	v_mfma_f32_16x16x32_bf16 v[122:125], v[172:175], v[196:199], v[122:125]
	v_mfma_f32_16x16x32_bf16 v[110:113], v[134:137], v[222:225], v[110:113]
	v_mfma_f32_16x16x32_bf16 v[106:109], v[172:175], v[222:225], v[106:109]
	v_mfma_f32_16x16x32_bf16 v[94:97], v[134:137], v[230:233], v[94:97]
	v_mfma_f32_16x16x32_bf16 v[90:93], v[172:175], v[230:233], v[90:93]
	v_mfma_f32_16x16x32_bf16 v[78:81], v[134:137], v[238:241], v[78:81]
	v_mfma_f32_16x16x32_bf16 v[74:77], v[172:175], v[238:241], v[74:77]
	s_setprio 0
	s_setprio 1
	v_mfma_f32_16x16x32_bf16 v[118:121], v[176:179], v[192:195], 0
	v_mfma_f32_16x16x32_bf16 v[114:117], v[184:187], v[192:195], 0
	v_mfma_f32_16x16x32_bf16 v[102:105], v[176:179], v[218:221], 0
	v_mfma_f32_16x16x32_bf16 v[98:101], v[184:187], v[218:221], 0
	v_mfma_f32_16x16x32_bf16 v[86:89], v[176:179], v[226:229], 0
	v_mfma_f32_16x16x32_bf16 v[82:85], v[184:187], v[226:229], 0
	v_mfma_f32_16x16x32_bf16 v[70:73], v[176:179], v[234:237], 0
	v_mfma_f32_16x16x32_bf16 v[66:69], v[184:187], v[234:237], 0
	v_mfma_f32_16x16x32_bf16 v[118:121], v[180:183], v[196:199], v[118:121]
	v_mfma_f32_16x16x32_bf16 v[114:117], v[188:191], v[196:199], v[114:117]
	v_mfma_f32_16x16x32_bf16 v[102:105], v[180:183], v[222:225], v[102:105]
	v_mfma_f32_16x16x32_bf16 v[98:101], v[188:191], v[222:225], v[98:101]
	v_mfma_f32_16x16x32_bf16 v[86:89], v[180:183], v[230:233], v[86:89]
	v_mfma_f32_16x16x32_bf16 v[82:85], v[188:191], v[230:233], v[82:85]
	v_mfma_f32_16x16x32_bf16 v[70:73], v[180:183], v[238:241], v[70:73]
	v_mfma_f32_16x16x32_bf16 v[66:69], v[188:191], v[238:241], v[66:69]
	s_setprio 0
	s_barrier
	s_add_i32 s17, s18, s78
	v_lshl_add_u64 v[200:201], s[42:43], 0, v[142:143]
	s_mov_b32 m0, s17
	ds_read_b128 v[192:195], v163 offset:16384
	ds_read_b128 v[196:199], v163 offset:17408
	ds_read_b128 v[218:221], v163 offset:18432
	ds_read_b128 v[222:225], v163 offset:19456
	ds_read_b128 v[226:229], v163 offset:20480
	ds_read_b128 v[230:233], v163 offset:21504
	ds_read_b128 v[234:237], v163 offset:22528
	ds_read_b128 v[238:241], v163 offset:23552
	global_load_lds_dwordx4 v[200:201], off
	s_add_i32 m0, s17, 0x2000
	s_add_u32 s22, s42, 0x40000
	v_lshl_add_u64 v[242:243], s[42:43], 0, v[138:139]
	s_addc_u32 s23, s43, 0
	s_add_i32 s6, s6, s78
	global_load_lds_dwordx4 v[242:243], off
	v_lshl_add_u64 v[244:245], s[22:23], 0, v[142:143]
	s_mov_b32 m0, s6
	v_lshl_add_u64 v[246:247], s[52:53], 0, v[140:141]
	global_load_lds_dwordx4 v[244:245], off
	v_lshl_add_u64 v[244:245], s[22:23], 0, v[138:139]
	s_add_i32 m0, s6, 0x2000
	s_nop 0
	global_load_lds_dwordx4 v[244:245], off
	v_lshl_add_u64 v[244:245], s[52:53], 0, v[0:1]
	s_mov_b32 m0, s79
	s_nop 0
	global_load_lds_dwordx4 v[244:245], off
	s_mov_b32 m0, s82
	s_nop 0
	global_load_lds_dwordx4 v[246:247], off
	s_waitcnt vmcnt(8)
	s_waitcnt lgkmcnt(0)
	s_barrier
; #define PG8_STAGE(bufoff, gbase, voff) do { _Pragma("unroll") for (int _i = 0; _i < 2; ++_i) \
;         __builtin_amdgcn_global_load_lds((const unsigned*)((const char*)(gbase) + (voff)[_i]), (LAS unsigned*)(lds + (bufoff) + ldsw + _i * 8192), 16, 0, 0); } while (0)
; #define PG8_LDA(dst, b, h) do { _Pragma("unroll") for (int m = 0; m < 4; ++m) _Pragma("unroll") for (int k = 0; k < 2; ++k) dst[m][k] = *(const LAS bf16x8*)(lds + PG8_SA(b, h) + aoff + m * 2048 + k * 1024); } while (0)
; #define PG8_LDB(dst, b, h) do { _Pragma("unroll") for (int n = 0; n < 2; ++n) _Pragma("unroll") for (int k = 0; k < 2; ++k) dst[n][k] = *(const LAS bf16x8*)(lds + PG8_SB(b, h) + boff + n * 2048 + k * 1024); } while (0)
; #define PG8_MMA(ai, bj, At, Bt) do { __builtin_amdgcn_s_setprio(1); _Pragma("unroll") for (int m = 0; m < 4; ++m) _Pragma("unroll") for (int n = 0; n < 2; ++n) _Pragma("unroll") for (int k = 0; k < 2; ++k) \
;         acc[ai][bj][m][n] = __builtin_amdgcn_mfma_f32_16x16x32_bf16(Bt[n][k], At[m][k], acc[ai][bj][m][n], 0, 0, 0); __builtin_amdgcn_s_setprio(0); } while (0)
; #define PG8_WAIT_V(n) asm volatile("s_waitcnt vmcnt(" #n ")" ::: "memory")
; #define PG8_WAIT_L(n) asm volatile("s_waitcnt lgkmcnt(" #n ")" ::: "memory")
; #define PG8_BAR __builtin_amdgcn_s_barrier()
; #define PG8_SCHED __builtin_amdgcn_sched_barrier(0)
; template <class Epi>
; DI void gemm_phase(LAS unsigned char* lds, const Gemm g, int G, int c, const Epi& E) {
;     ...
;             PG8_WAIT_V(8); PG8_WAIT_L(0); PG8_BAR; PG8_MMA(1, 0, At, B0); PG8_MMA(1, 1, At, B1); PG8_BAR; PG8_SCHED;
;             PG8_LDB(B0, 1, 0); PG8_LDB(B1, 1, 1); PG8_SCHED; PG8_LDA(At, 1, 0); PG8_STAGE(PG8_SA(0, 1), a2 + hstepA, voffA);
;             PG8_WAIT_V(8); PG8_WAIT_L(0); PG8_BAR; PG8_MMA(0, 0, At, B0); PG8_MMA(0, 1, At, B1); PG8_BAR; PG8_SCHED;
	s_setprio 1
	s_waitcnt lgkmcnt(0)
	v_mfma_f32_16x16x32_bf16 v[62:65], v[130:133], v[192:195], 0
	v_mfma_f32_16x16x32_bf16 v[58:61], v[150:153], v[192:195], 0
	v_mfma_f32_16x16x32_bf16 v[46:49], v[130:133], v[218:221], 0
	v_mfma_f32_16x16x32_bf16 v[42:45], v[150:153], v[218:221], 0
	v_mfma_f32_16x16x32_bf16 v[30:33], v[130:133], v[226:229], 0
	v_mfma_f32_16x16x32_bf16 v[26:29], v[150:153], v[226:229], 0
	v_mfma_f32_16x16x32_bf16 v[14:17], v[130:133], v[234:237], 0
	v_mfma_f32_16x16x32_bf16 v[10:13], v[150:153], v[234:237], 0
	v_mfma_f32_16x16x32_bf16 v[62:65], v[134:137], v[196:199], v[62:65]
	v_mfma_f32_16x16x32_bf16 v[58:61], v[172:175], v[196:199], v[58:61]
	v_mfma_f32_16x16x32_bf16 v[46:49], v[134:137], v[222:225], v[46:49]
	v_mfma_f32_16x16x32_bf16 v[42:45], v[172:175], v[222:225], v[42:45]
	v_mfma_f32_16x16x32_bf16 v[30:33], v[134:137], v[230:233], v[30:33]
	v_mfma_f32_16x16x32_bf16 v[26:29], v[172:175], v[230:233], v[26:29]
	v_mfma_f32_16x16x32_bf16 v[14:17], v[134:137], v[238:241], v[14:17]
	v_mfma_f32_16x16x32_bf16 v[10:13], v[172:175], v[238:241], v[10:13]
	s_setprio 0
	s_setprio 1
	v_mfma_f32_16x16x32_bf16 v[54:57], v[176:179], v[192:195], 0
	v_mfma_f32_16x16x32_bf16 v[50:53], v[184:187], v[192:195], 0
	v_mfma_f32_16x16x32_bf16 v[38:41], v[176:179], v[218:221], 0
	v_mfma_f32_16x16x32_bf16 v[34:37], v[184:187], v[218:221], 0
	v_mfma_f32_16x16x32_bf16 v[22:25], v[176:179], v[226:229], 0
	v_mfma_f32_16x16x32_bf16 v[18:21], v[184:187], v[226:229], 0
	v_mfma_f32_16x16x32_bf16 v[6:9], v[176:179], v[234:237], 0
	v_mfma_f32_16x16x32_bf16 v[2:5], v[184:187], v[234:237], 0
	v_mfma_f32_16x16x32_bf16 v[54:57], v[180:183], v[196:199], v[54:57]
	v_mfma_f32_16x16x32_bf16 v[50:53], v[188:191], v[196:199], v[50:53]
	v_mfma_f32_16x16x32_bf16 v[38:41], v[180:183], v[222:225], v[38:41]
	v_mfma_f32_16x16x32_bf16 v[34:37], v[188:191], v[222:225], v[34:37]
	v_mfma_f32_16x16x32_bf16 v[22:25], v[180:183], v[230:233], v[22:25]
	v_mfma_f32_16x16x32_bf16 v[18:21], v[188:191], v[230:233], v[18:21]
	v_mfma_f32_16x16x32_bf16 v[6:9], v[180:183], v[238:241], v[6:9]
	v_mfma_f32_16x16x32_bf16 v[2:5], v[188:191], v[238:241], v[2:5]
	s_setprio 0
	s_barrier
	s_add_i32 s6, 0, 0x18000
	s_add_i32 s17, 0, 0x1c000
	v_add_u32_e32 v172, s6, v155
	v_add_u32_e32 v188, s17, v155
	ds_read_b128 v[130:133], v172
	ds_read_b128 v[134:137], v172 offset:1024
	ds_read_b128 v[150:153], v172 offset:2048
	ds_read_b128 v[172:175], v172 offset:3072
	ds_read_b128 v[176:179], v188
	ds_read_b128 v[180:183], v188 offset:1024
	ds_read_b128 v[184:187], v188 offset:2048
	ds_read_b128 v[188:191], v188 offset:3072
	s_add_u32 s22, s52, 0x40000
	s_addc_u32 s23, s53, 0
	s_mov_b32 m0, s83
	v_lshl_add_u64 v[248:249], s[22:23], 0, v[0:1]
	ds_read_b128 v[192:195], v163 offset:32768
	ds_read_b128 v[196:199], v163 offset:33792
	ds_read_b128 v[218:221], v163 offset:34816
	ds_read_b128 v[222:225], v163 offset:35840
	ds_read_b128 v[226:229], v163 offset:36864
	ds_read_b128 v[230:233], v163 offset:37888
	ds_read_b128 v[234:237], v163 offset:38912
	ds_read_b128 v[238:241], v163 offset:39936
	global_load_lds_dwordx4 v[248:249], off
	v_lshl_add_u64 v[248:249], s[22:23], 0, v[140:141]
	s_mov_b32 m0, s84
	s_nop 0
	global_load_lds_dwordx4 v[248:249], off
	s_waitcnt vmcnt(8)
	s_waitcnt lgkmcnt(0)
	s_barrier
	s_setprio 1
	s_waitcnt lgkmcnt(0)
	v_mfma_f32_16x16x32_bf16 v[126:129], v[130:133], v[192:195], v[126:129]
	v_mfma_f32_16x16x32_bf16 v[122:125], v[150:153], v[192:195], v[122:125]
	v_mfma_f32_16x16x32_bf16 v[110:113], v[130:133], v[218:221], v[110:113]
	v_mfma_f32_16x16x32_bf16 v[106:109], v[150:153], v[218:221], v[106:109]
	v_mfma_f32_16x16x32_bf16 v[94:97], v[130:133], v[226:229], v[94:97]
	v_mfma_f32_16x16x32_bf16 v[90:93], v[150:153], v[226:229], v[90:93]
	v_mfma_f32_16x16x32_bf16 v[78:81], v[130:133], v[234:237], v[78:81]
	v_mfma_f32_16x16x32_bf16 v[74:77], v[150:153], v[234:237], v[74:77]
	v_mfma_f32_16x16x32_bf16 v[126:129], v[134:137], v[196:199], v[126:129]
	v_mfma_f32_16x16x32_bf16 v[122:125], v[172:175], v[196:199], v[122:125]
	v_mfma_f32_16x16x32_bf16 v[110:113], v[134:137], v[222:225], v[110:113]
	v_mfma_f32_16x16x32_bf16 v[106:109], v[172:175], v[222:225], v[106:109]
	v_mfma_f32_16x16x32_bf16 v[94:97], v[134:137], v[230:233], v[94:97]
	v_mfma_f32_16x16x32_bf16 v[90:93], v[172:175], v[230:233], v[90:93]
	v_mfma_f32_16x16x32_bf16 v[78:81], v[134:137], v[238:241], v[78:81]
	v_mfma_f32_16x16x32_bf16 v[74:77], v[172:175], v[238:241], v[74:77]
	s_setprio 0
	s_setprio 1
	v_mfma_f32_16x16x32_bf16 v[118:121], v[176:179], v[192:195], v[118:121]
	v_mfma_f32_16x16x32_bf16 v[114:117], v[184:187], v[192:195], v[114:117]
	v_mfma_f32_16x16x32_bf16 v[102:105], v[176:179], v[218:221], v[102:105]
	v_mfma_f32_16x16x32_bf16 v[98:101], v[184:187], v[218:221], v[98:101]
	v_mfma_f32_16x16x32_bf16 v[86:89], v[176:179], v[226:229], v[86:89]
	v_mfma_f32_16x16x32_bf16 v[82:85], v[184:187], v[226:229], v[82:85]
	v_mfma_f32_16x16x32_bf16 v[70:73], v[176:179], v[234:237], v[70:73]
	v_mfma_f32_16x16x32_bf16 v[66:69], v[184:187], v[234:237], v[66:69]
	v_mfma_f32_16x16x32_bf16 v[118:121], v[180:183], v[196:199], v[118:121]
	v_mfma_f32_16x16x32_bf16 v[114:117], v[188:191], v[196:199], v[114:117]
	v_mfma_f32_16x16x32_bf16 v[102:105], v[180:183], v[222:225], v[102:105]
	v_mfma_f32_16x16x32_bf16 v[98:101], v[188:191], v[222:225], v[98:101]
	v_mfma_f32_16x16x32_bf16 v[86:89], v[180:183], v[230:233], v[86:89]
	v_mfma_f32_16x16x32_bf16 v[82:85], v[188:191], v[230:233], v[82:85]
	v_mfma_f32_16x16x32_bf16 v[70:73], v[180:183], v[238:241], v[70:73]
	v_mfma_f32_16x16x32_bf16 v[66:69], v[188:191], v[238:241], v[66:69]
	s_setprio 0
	s_barrier
; #define PG8_STAGE(bufoff, gbase, voff) do { _Pragma("unroll") for (int _i = 0; _i < 2; ++_i) \
;         __builtin_amdgcn_global_load_lds((const unsigned*)((const char*)(gbase) + (voff)[_i]), (LAS unsigned*)(lds + (bufoff) + ldsw + _i * 8192), 16, 0, 0); } while (0)
; #define PG8_LDA(dst, b, h) do { _Pragma("unroll") for (int m = 0; m < 4; ++m) _Pragma("unroll") for (int k = 0; k < 2; ++k) dst[m][k] = *(const LAS bf16x8*)(lds + PG8_SA(b, h) + aoff + m * 2048 + k * 1024); } while (0)
; #define PG8_MMA(ai, bj, At, Bt) do { __builtin_amdgcn_s_setprio(1); _Pragma("unroll") for (int m = 0; m < 4; ++m) _Pragma("unroll") for (int n = 0; n < 2; ++n) _Pragma("unroll") for (int k = 0; k < 2; ++k) \
;         acc[ai][bj][m][n] = __builtin_amdgcn_mfma_f32_16x16x32_bf16(Bt[n][k], At[m][k], acc[ai][bj][m][n], 0, 0, 0); __builtin_amdgcn_s_setprio(0); } while (0)
; #define PG8_WAIT_V(n) asm volatile("s_waitcnt vmcnt(" #n ")" ::: "memory")
; #define PG8_WAIT_L(n) asm volatile("s_waitcnt lgkmcnt(" #n ")" ::: "memory")
; #define PG8_BAR __builtin_amdgcn_s_barrier()
; #define PG8_SCHED __builtin_amdgcn_sched_barrier(0)
; template <class Epi>
; DI void gemm_phase(LAS unsigned char* lds, const Gemm g, int G, int c, const Epi& E) {
;     ...
;             PG8_LDA(At, 1, 1); PG8_STAGE(PG8_SB(1, 0), b3, voffB); PG8_STAGE(PG8_SB(1, 1), b3 + hstepB, voffB); PG8_STAGE(PG8_SA(1, 0), a3, voffA);
;             PG8_WAIT_V(8); PG8_WAIT_L(0); PG8_BAR; PG8_MMA(1, 0, At, B0); PG8_MMA(1, 1, At, B1); PG8_BAR; PG8_SCHED;
;         }
	s_add_i32 s6, s6, s78
	v_lshl_add_u64 v[200:201], v[200:201], 0, s[14:15]
	s_mov_b32 m0, s6
	ds_read_b128 v[192:195], v163 offset:49152
	ds_read_b128 v[196:199], v163 offset:50176
	ds_read_b128 v[218:221], v163 offset:51200
	ds_read_b128 v[222:225], v163 offset:52224
	ds_read_b128 v[226:229], v163 offset:53248
	ds_read_b128 v[230:233], v163 offset:54272
	ds_read_b128 v[234:237], v163 offset:55296
	ds_read_b128 v[238:241], v163 offset:56320
	global_load_lds_dwordx4 v[200:201], off
	s_add_i32 m0, s6, 0x2000
	s_add_u32 s22, s42, 0x40080
	v_lshl_add_u64 v[200:201], v[242:243], 0, s[14:15]
	s_addc_u32 s23, s43, 0
	s_add_i32 s6, s17, s78
	global_load_lds_dwordx4 v[200:201], off
	v_lshl_add_u64 v[200:201], s[22:23], 0, v[142:143]
	s_mov_b32 m0, s6
	s_nop 0
	global_load_lds_dwordx4 v[200:201], off
	v_lshl_add_u64 v[200:201], s[22:23], 0, v[138:139]
	s_add_i32 m0, s6, 0x2000
	s_nop 0
	global_load_lds_dwordx4 v[200:201], off
	v_lshl_add_u64 v[200:201], v[244:245], 0, s[14:15]
	s_mov_b32 m0, s85
	s_nop 0
	global_load_lds_dwordx4 v[200:201], off
	v_lshl_add_u64 v[200:201], v[246:247], 0, s[14:15]
	s_mov_b32 m0, s97
	s_nop 0
	global_load_lds_dwordx4 v[200:201], off
	s_waitcnt vmcnt(8)
	s_waitcnt lgkmcnt(0)
	s_barrier
	s_setprio 1
	s_waitcnt lgkmcnt(0)
	v_mfma_f32_16x16x32_bf16 v[62:65], v[130:133], v[192:195], v[62:65]
	v_mfma_f32_16x16x32_bf16 v[58:61], v[150:153], v[192:195], v[58:61]
	v_mfma_f32_16x16x32_bf16 v[46:49], v[130:133], v[218:221], v[46:49]
	v_mfma_f32_16x16x32_bf16 v[42:45], v[150:153], v[218:221], v[42:45]
	v_mfma_f32_16x16x32_bf16 v[30:33], v[130:133], v[226:229], v[30:33]
	v_mfma_f32_16x16x32_bf16 v[26:29], v[150:153], v[226:229], v[26:29]
	v_mfma_f32_16x16x32_bf16 v[14:17], v[130:133], v[234:237], v[14:17]
	v_mfma_f32_16x16x32_bf16 v[10:13], v[150:153], v[234:237], v[10:13]
	v_mfma_f32_16x16x32_bf16 v[62:65], v[134:137], v[196:199], v[62:65]
	v_mfma_f32_16x16x32_bf16 v[58:61], v[172:175], v[196:199], v[58:61]
	v_mfma_f32_16x16x32_bf16 v[46:49], v[134:137], v[222:225], v[46:49]
	v_mfma_f32_16x16x32_bf16 v[42:45], v[172:175], v[222:225], v[42:45]
	v_mfma_f32_16x16x32_bf16 v[30:33], v[134:137], v[230:233], v[30:33]
	v_mfma_f32_16x16x32_bf16 v[26:29], v[172:175], v[230:233], v[26:29]
	v_mfma_f32_16x16x32_bf16 v[14:17], v[134:137], v[238:241], v[14:17]
	v_mfma_f32_16x16x32_bf16 v[10:13], v[172:175], v[238:241], v[10:13]
	s_setprio 0
	s_setprio 1
	v_mfma_f32_16x16x32_bf16 v[54:57], v[176:179], v[192:195], v[54:57]
	v_mfma_f32_16x16x32_bf16 v[50:53], v[184:187], v[192:195], v[50:53]
	v_mfma_f32_16x16x32_bf16 v[38:41], v[176:179], v[218:221], v[38:41]
	v_mfma_f32_16x16x32_bf16 v[34:37], v[184:187], v[218:221], v[34:37]
	v_mfma_f32_16x16x32_bf16 v[22:25], v[176:179], v[226:229], v[22:25]
	v_mfma_f32_16x16x32_bf16 v[18:21], v[184:187], v[226:229], v[18:21]
	v_mfma_f32_16x16x32_bf16 v[6:9], v[176:179], v[234:237], v[6:9]
	v_mfma_f32_16x16x32_bf16 v[2:5], v[184:187], v[234:237], v[2:5]
	v_mfma_f32_16x16x32_bf16 v[54:57], v[180:183], v[196:199], v[54:57]
	v_mfma_f32_16x16x32_bf16 v[50:53], v[188:191], v[196:199], v[50:53]
	v_mfma_f32_16x16x32_bf16 v[38:41], v[180:183], v[222:225], v[38:41]
	v_mfma_f32_16x16x32_bf16 v[34:37], v[188:191], v[222:225], v[34:37]
	v_mfma_f32_16x16x32_bf16 v[22:25], v[180:183], v[230:233], v[22:25]
	v_mfma_f32_16x16x32_bf16 v[18:21], v[188:191], v[230:233], v[18:21]
	v_mfma_f32_16x16x32_bf16 v[6:9], v[180:183], v[238:241], v[6:9]
	v_mfma_f32_16x16x32_bf16 v[2:5], v[188:191], v[238:241], v[2:5]
	s_setprio 0
	s_barrier
	s_add_i32 s38, s38, 2
	s_add_u32 s0, s0, 0x100
	s_addc_u32 s1, s1, 0
	s_add_u32 s30, s30, 0x100
	s_addc_u32 s31, s31, 0
	s_cmp_gt_u32 s38, 13
	s_nop 0
	s_nop 0
	s_nop 0
	s_nop 0
